# priority raise kept through the latency-bound P7 merge epilogue (reset after it instead of at K-loop exit)
# baseline (speedup 1.0000x reference)
; #define PG8_STAGE(bufoff, gbase, voff) do { _Pragma("unroll") for (int _i = 0; _i < 2; ++_i) \
;         __builtin_amdgcn_global_load_lds((const unsigned*)((const char*)(gbase) + (voff)[_i]), (LAS unsigned*)(lds + (bufoff) + ldsw + _i * 8192), 16, 0, 0); } while (0)
; #define PG8_LDA(dst, b, h) do { _Pragma("unroll") for (int m = 0; m < 4; ++m) _Pragma("unroll") for (int k = 0; k < 2; ++k) dst[m][k] = *(const LAS bf16x8*)(lds + PG8_SA(b, h) + aoff + m * 2048 + k * 1024); } while (0)
; #define PG8_LDB(dst, b, h) do { _Pragma("unroll") for (int n = 0; n < 2; ++n) _Pragma("unroll") for (int k = 0; k < 2; ++k) dst[n][k] = *(const LAS bf16x8*)(lds + PG8_SB(b, h) + boff + n * 2048 + k * 1024); } while (0)
; #define PG8_MMA(ai, bj, At, Bt) do { __builtin_amdgcn_s_setprio(1); _Pragma("unroll") for (int m = 0; m < 4; ++m) _Pragma("unroll") for (int n = 0; n < 2; ++n) _Pragma("unroll") for (int k = 0; k < 2; ++k) \
;         acc[ai][bj][m][n] = __builtin_amdgcn_mfma_f32_16x16x32_bf16(Bt[n][k], At[m][k], acc[ai][bj][m][n], 0, 0, 0); __builtin_amdgcn_s_setprio(0); } while (0)
; #define PG8_WAIT_V(n) asm volatile("s_waitcnt vmcnt(" #n ")" ::: "memory")
; #define PG8_WAIT_L(n) asm volatile("s_waitcnt lgkmcnt(" #n ")" ::: "memory")
; #define PG8_BAR __builtin_amdgcn_s_barrier()
; #define PG8_SCHED __builtin_amdgcn_sched_barrier(0)
; template <class Sched, class Epi, bool ALIGN_EPI, bool SP2>
; __device__ __forceinline__ void gemm_phase(LAS unsigned char* lds, const int K, const int lda, const int ldb, const Sched& S, const Epi& E) {
;     ...
;             PG8_LDB(B0, 0, 0); PG8_LDB(B1, 0, 1); PG8_SCHED; PG8_LDA(At, 0, 0); PG8_STAGE(PG8_SA(1, 1), a1 + hstepA, voffA);
;             PG8_WAIT_V(8); PG8_WAIT_L(0); PG8_BAR; PG8_MMA(0, 0, At, B0); PG8_MMA(0, 1, At, B1); PG8_BAR; PG8_SCHED;
;             PG8_LDA(At, 0, 1); PG8_STAGE(PG8_SB(0, 0), b2, voffB); PG8_STAGE(PG8_SB(0, 1), b2 + hstepB, voffB); PG8_STAGE(PG8_SA(0, 0), a2, voffA);
;             PG8_WAIT_V(8); PG8_WAIT_L(0); PG8_BAR; PG8_MMA(1, 0, At, B0); PG8_MMA(1, 1, At, B1); PG8_BAR; PG8_SCHED;
.Lprio_skip_821:
.LBB0_821:
	v_add_u32_e32 v140, s44, v181
	v_add_u32_e32 v170, s45, v181
	ds_read_b128 v[128:131], v140
	ds_read_b128 v[132:135], v140 offset:1024
	ds_read_b128 v[136:139], v140 offset:2048
	ds_read_b128 v[140:143], v140 offset:3072
	ds_read_b128 v[144:147], v170
	ds_read_b128 v[148:151], v170 offset:1024
	ds_read_b128 v[166:169], v170 offset:2048
	ds_read_b128 v[170:173], v170 offset:3072
	s_add_u32 s20, s4, 0x100
	s_addc_u32 s21, s5, 0
	s_cmp_eq_u32 s61, 12
	s_cselect_b32 s25, s15, s21
	s_cselect_b32 s24, s14, s20
	s_cselect_b32 s23, s17, s60
	s_cselect_b32 s22, s16, s53
	s_add_i32 m0, s29, 0xc000
	ds_read_b128 v[184:187], v183
	ds_read_b128 v[188:191], v183 offset:1024
	ds_read_b128 v[192:195], v183 offset:2048
	ds_read_b128 v[196:199], v183 offset:3072
	ds_read_b128 v[200:203], v183 offset:4096
	ds_read_b128 v[204:207], v183 offset:5120
	ds_read_b128 v[208:211], v183 offset:6144
	ds_read_b128 v[212:215], v183 offset:7168
	global_load_lds_dwordx4 v162, s[4:5]
	s_add_i32 m0, s29, 0xe000
	s_nop 0
	global_load_lds_dwordx4 v164, s[4:5]
	s_waitcnt vmcnt(8) lgkmcnt(0)
	s_barrier
	v_mfma_f32_16x16x32_bf16 v[124:127], v[128:131], v[184:187], v[124:127]
	v_mfma_f32_16x16x32_bf16 v[120:123], v[136:139], v[184:187], v[120:123]
	v_mfma_f32_16x16x32_bf16 v[116:119], v[128:131], v[192:195], v[116:119]
	v_mfma_f32_16x16x32_bf16 v[112:115], v[136:139], v[192:195], v[112:115]
	v_mfma_f32_16x16x32_bf16 v[108:111], v[128:131], v[200:203], v[108:111]
	v_mfma_f32_16x16x32_bf16 v[104:107], v[136:139], v[200:203], v[104:107]
	v_mfma_f32_16x16x32_bf16 v[100:103], v[128:131], v[208:211], v[100:103]
	v_mfma_f32_16x16x32_bf16 v[96:99], v[136:139], v[208:211], v[96:99]
	v_mfma_f32_16x16x32_bf16 v[124:127], v[132:135], v[188:191], v[124:127]
	v_mfma_f32_16x16x32_bf16 v[120:123], v[140:143], v[188:191], v[120:123]
	v_mfma_f32_16x16x32_bf16 v[116:119], v[132:135], v[196:199], v[116:119]
	v_mfma_f32_16x16x32_bf16 v[112:115], v[140:143], v[196:199], v[112:115]
	v_mfma_f32_16x16x32_bf16 v[108:111], v[132:135], v[204:207], v[108:111]
	v_mfma_f32_16x16x32_bf16 v[104:107], v[140:143], v[204:207], v[104:107]
	v_mfma_f32_16x16x32_bf16 v[100:103], v[132:135], v[212:215], v[100:103]
	v_mfma_f32_16x16x32_bf16 v[96:99], v[140:143], v[212:215], v[96:99]
	v_mfma_f32_16x16x32_bf16 v[92:95], v[144:147], v[184:187], v[92:95]
	v_mfma_f32_16x16x32_bf16 v[88:91], v[166:169], v[184:187], v[88:91]
	v_mfma_f32_16x16x32_bf16 v[84:87], v[144:147], v[192:195], v[84:87]
	v_mfma_f32_16x16x32_bf16 v[80:83], v[166:169], v[192:195], v[80:83]
	v_mfma_f32_16x16x32_bf16 v[76:79], v[144:147], v[200:203], v[76:79]
	v_mfma_f32_16x16x32_bf16 v[72:75], v[166:169], v[200:203], v[72:75]
	v_mfma_f32_16x16x32_bf16 v[68:71], v[144:147], v[208:211], v[68:71]
	v_mfma_f32_16x16x32_bf16 v[64:67], v[166:169], v[208:211], v[64:67]
	v_mfma_f32_16x16x32_bf16 v[92:95], v[148:151], v[188:191], v[92:95]
	v_mfma_f32_16x16x32_bf16 v[88:91], v[170:173], v[188:191], v[88:91]
	v_mfma_f32_16x16x32_bf16 v[84:87], v[148:151], v[196:199], v[84:87]
	v_mfma_f32_16x16x32_bf16 v[80:83], v[170:173], v[196:199], v[80:83]
	v_mfma_f32_16x16x32_bf16 v[76:79], v[148:151], v[204:207], v[76:79]
	v_mfma_f32_16x16x32_bf16 v[72:75], v[170:173], v[204:207], v[72:75]
	v_mfma_f32_16x16x32_bf16 v[68:71], v[148:151], v[212:215], v[68:71]
	v_mfma_f32_16x16x32_bf16 v[64:67], v[170:173], v[212:215], v[64:67]
	s_barrier
	s_add_i32 s4, s44, s28
	v_lshl_add_u64 v[174:175], s[22:23], 0, v[156:157]
	s_mov_b32 m0, s4
	ds_read_b128 v[184:187], v183 offset:16384
	ds_read_b128 v[188:191], v183 offset:17408
	ds_read_b128 v[192:195], v183 offset:18432
	ds_read_b128 v[196:199], v183 offset:19456
	ds_read_b128 v[200:203], v183 offset:20480
	ds_read_b128 v[204:207], v183 offset:21504
	ds_read_b128 v[208:211], v183 offset:22528
	ds_read_b128 v[212:215], v183 offset:23552
	global_load_lds_dwordx4 v[174:175], off
	s_add_i32 m0, s4, 0x2000
	s_add_u32 s4, s22, 0x40000
	v_lshl_add_u64 v[216:217], s[22:23], 0, v[160:161]
	s_addc_u32 s5, s23, 0
	s_add_i32 s62, s45, s28
	global_load_lds_dwordx4 v[216:217], off
	s_mov_b32 m0, s62
	v_lshl_add_u64 v[220:221], s[24:25], 0, v[158:159]
	global_load_lds_dwordx4 v156, s[4:5]
	s_add_i32 m0, s62, 0x2000
	s_nop 0
	global_load_lds_dwordx4 v160, s[4:5]
	v_lshl_add_u64 v[218:219], s[24:25], 0, v[154:155]
	s_mov_b32 m0, s29
	s_nop 0
	global_load_lds_dwordx4 v[218:219], off
	s_mov_b32 m0, s33
	s_nop 0
	global_load_lds_dwordx4 v[220:221], off
	s_waitcnt vmcnt(8) lgkmcnt(0)
	s_barrier
	v_mfma_f32_16x16x32_bf16 v[60:63], v[128:131], v[184:187], v[60:63]
	v_mfma_f32_16x16x32_bf16 v[56:59], v[136:139], v[184:187], v[56:59]
	v_mfma_f32_16x16x32_bf16 v[52:55], v[128:131], v[192:195], v[52:55]
	v_mfma_f32_16x16x32_bf16 v[48:51], v[136:139], v[192:195], v[48:51]
	v_mfma_f32_16x16x32_bf16 v[44:47], v[128:131], v[200:203], v[44:47]
	v_mfma_f32_16x16x32_bf16 v[40:43], v[136:139], v[200:203], v[40:43]
	v_mfma_f32_16x16x32_bf16 v[36:39], v[128:131], v[208:211], v[36:39]
	v_mfma_f32_16x16x32_bf16 v[32:35], v[136:139], v[208:211], v[32:35]
	v_mfma_f32_16x16x32_bf16 v[60:63], v[132:135], v[188:191], v[60:63]
	v_mfma_f32_16x16x32_bf16 v[56:59], v[140:143], v[188:191], v[56:59]
	v_mfma_f32_16x16x32_bf16 v[52:55], v[132:135], v[196:199], v[52:55]
	v_mfma_f32_16x16x32_bf16 v[48:51], v[140:143], v[196:199], v[48:51]
	v_mfma_f32_16x16x32_bf16 v[44:47], v[132:135], v[204:207], v[44:47]
	v_mfma_f32_16x16x32_bf16 v[40:43], v[140:143], v[204:207], v[40:43]
	v_mfma_f32_16x16x32_bf16 v[36:39], v[132:135], v[212:215], v[36:39]
	v_mfma_f32_16x16x32_bf16 v[32:35], v[140:143], v[212:215], v[32:35]
	v_mfma_f32_16x16x32_bf16 v[28:31], v[144:147], v[184:187], v[28:31]
	v_mfma_f32_16x16x32_bf16 v[24:27], v[166:169], v[184:187], v[24:27]
	v_mfma_f32_16x16x32_bf16 v[20:23], v[144:147], v[192:195], v[20:23]
	v_mfma_f32_16x16x32_bf16 v[16:19], v[166:169], v[192:195], v[16:19]
	v_mfma_f32_16x16x32_bf16 v[12:15], v[144:147], v[200:203], v[12:15]
	v_mfma_f32_16x16x32_bf16 v[8:11], v[166:169], v[200:203], v[8:11]
	v_mfma_f32_16x16x32_bf16 v[4:7], v[144:147], v[208:211], v[4:7]
	v_mfma_f32_16x16x32_bf16 v[0:3], v[166:169], v[208:211], v[0:3]
	v_mfma_f32_16x16x32_bf16 v[28:31], v[148:151], v[188:191], v[28:31]
	v_mfma_f32_16x16x32_bf16 v[24:27], v[170:173], v[188:191], v[24:27]
	v_mfma_f32_16x16x32_bf16 v[20:23], v[148:151], v[196:199], v[20:23]
	v_mfma_f32_16x16x32_bf16 v[16:19], v[170:173], v[196:199], v[16:19]
	v_mfma_f32_16x16x32_bf16 v[12:15], v[148:151], v[204:207], v[12:15]
	v_mfma_f32_16x16x32_bf16 v[8:11], v[170:173], v[204:207], v[8:11]
	v_mfma_f32_16x16x32_bf16 v[4:7], v[148:151], v[212:215], v[4:7]
	v_mfma_f32_16x16x32_bf16 v[0:3], v[170:173], v[212:215], v[0:3]
	s_barrier
; #define PG8_STAGE(bufoff, gbase, voff) do { _Pragma("unroll") for (int _i = 0; _i < 2; ++_i) \
;         __builtin_amdgcn_global_load_lds((const unsigned*)((const char*)(gbase) + (voff)[_i]), (LAS unsigned*)(lds + (bufoff) + ldsw + _i * 8192), 16, 0, 0); } while (0)
; #define PG8_LDA(dst, b, h) do { _Pragma("unroll") for (int m = 0; m < 4; ++m) _Pragma("unroll") for (int k = 0; k < 2; ++k) dst[m][k] = *(const LAS bf16x8*)(lds + PG8_SA(b, h) + aoff + m * 2048 + k * 1024); } while (0)
; #define PG8_LDB(dst, b, h) do { _Pragma("unroll") for (int n = 0; n < 2; ++n) _Pragma("unroll") for (int k = 0; k < 2; ++k) dst[n][k] = *(const LAS bf16x8*)(lds + PG8_SB(b, h) + boff + n * 2048 + k * 1024); } while (0)
; #define PG8_MMA(ai, bj, At, Bt) do { __builtin_amdgcn_s_setprio(1); _Pragma("unroll") for (int m = 0; m < 4; ++m) _Pragma("unroll") for (int n = 0; n < 2; ++n) _Pragma("unroll") for (int k = 0; k < 2; ++k) \
;         acc[ai][bj][m][n] = __builtin_amdgcn_mfma_f32_16x16x32_bf16(Bt[n][k], At[m][k], acc[ai][bj][m][n], 0, 0, 0); __builtin_amdgcn_s_setprio(0); } while (0)
; #define PG8_WAIT_V(n) asm volatile("s_waitcnt vmcnt(" #n ")" ::: "memory")
; #define PG8_WAIT_L(n) asm volatile("s_waitcnt lgkmcnt(" #n ")" ::: "memory")
; #define PG8_BAR __builtin_amdgcn_s_barrier()
; #define PG8_SCHED __builtin_amdgcn_sched_barrier(0)
; template <class Sched, class Epi, bool ALIGN_EPI, bool SP2>
; __device__ __forceinline__ void gemm_phase(LAS unsigned char* lds, const int K, const int lda, const int ldb, const Sched& S, const Epi& E) {
;     ...
;             PG8_LDB(B0, 1, 0); PG8_LDB(B1, 1, 1); PG8_SCHED; PG8_LDA(At, 1, 0); PG8_STAGE(PG8_SA(0, 1), a2 + hstepA, voffA);
;             PG8_WAIT_V(8); PG8_WAIT_L(0); PG8_BAR; PG8_MMA(0, 0, At, B0); PG8_MMA(0, 1, At, B1); PG8_BAR; PG8_SCHED;
;             PG8_LDA(At, 1, 1); PG8_STAGE(PG8_SB(1, 0), b3, voffB); PG8_STAGE(PG8_SB(1, 1), b3 + hstepB, voffB); PG8_STAGE(PG8_SA(1, 0), a3, voffA);
;             PG8_WAIT_V(8); PG8_WAIT_L(0); PG8_BAR; PG8_MMA(1, 0, At, B0); PG8_MMA(1, 1, At, B1); PG8_BAR; PG8_SCHED;
;     ...
;         if constexpr (ALIGN_EPI) { if (wr == 0) PG8_BAR; }
	s_add_i32 s62, 0, 0x18000
	s_add_i32 s63, 0, 0x1c000
	v_add_u32_e32 v140, s62, v181
	v_add_u32_e32 v170, s63, v181
	ds_read_b128 v[128:131], v140
	ds_read_b128 v[132:135], v140 offset:1024
	ds_read_b128 v[136:139], v140 offset:2048
	ds_read_b128 v[140:143], v140 offset:3072
	ds_read_b128 v[144:147], v170
	ds_read_b128 v[148:151], v170 offset:1024
	ds_read_b128 v[166:169], v170 offset:2048
	ds_read_b128 v[170:173], v170 offset:3072
	s_add_u32 s4, s24, 0xc0000
	s_addc_u32 s5, s25, 0
	s_mov_b32 m0, s35
	ds_read_b128 v[184:187], v183 offset:32768
	ds_read_b128 v[188:191], v183 offset:33792
	ds_read_b128 v[192:195], v183 offset:34816
	ds_read_b128 v[196:199], v183 offset:35840
	ds_read_b128 v[200:203], v183 offset:36864
	ds_read_b128 v[204:207], v183 offset:37888
	ds_read_b128 v[208:211], v183 offset:38912
	ds_read_b128 v[212:215], v183 offset:39936
	global_load_lds_dwordx4 v154, s[4:5]
	s_mov_b32 m0, s36
	s_nop 0
	global_load_lds_dwordx4 v158, s[4:5]
	s_waitcnt vmcnt(8) lgkmcnt(0)
	s_barrier
	v_mfma_f32_16x16x32_bf16 v[124:127], v[128:131], v[184:187], v[124:127]
	v_mfma_f32_16x16x32_bf16 v[120:123], v[136:139], v[184:187], v[120:123]
	v_mfma_f32_16x16x32_bf16 v[116:119], v[128:131], v[192:195], v[116:119]
	v_mfma_f32_16x16x32_bf16 v[112:115], v[136:139], v[192:195], v[112:115]
	v_mfma_f32_16x16x32_bf16 v[108:111], v[128:131], v[200:203], v[108:111]
	v_mfma_f32_16x16x32_bf16 v[104:107], v[136:139], v[200:203], v[104:107]
	v_mfma_f32_16x16x32_bf16 v[100:103], v[128:131], v[208:211], v[100:103]
	v_mfma_f32_16x16x32_bf16 v[96:99], v[136:139], v[208:211], v[96:99]
	v_mfma_f32_16x16x32_bf16 v[124:127], v[132:135], v[188:191], v[124:127]
	v_mfma_f32_16x16x32_bf16 v[120:123], v[140:143], v[188:191], v[120:123]
	v_mfma_f32_16x16x32_bf16 v[116:119], v[132:135], v[196:199], v[116:119]
	v_mfma_f32_16x16x32_bf16 v[112:115], v[140:143], v[196:199], v[112:115]
	v_mfma_f32_16x16x32_bf16 v[108:111], v[132:135], v[204:207], v[108:111]
	v_mfma_f32_16x16x32_bf16 v[104:107], v[140:143], v[204:207], v[104:107]
	v_mfma_f32_16x16x32_bf16 v[100:103], v[132:135], v[212:215], v[100:103]
	v_mfma_f32_16x16x32_bf16 v[96:99], v[140:143], v[212:215], v[96:99]
	v_mfma_f32_16x16x32_bf16 v[92:95], v[144:147], v[184:187], v[92:95]
	v_mfma_f32_16x16x32_bf16 v[88:91], v[166:169], v[184:187], v[88:91]
	v_mfma_f32_16x16x32_bf16 v[84:87], v[144:147], v[192:195], v[84:87]
	v_mfma_f32_16x16x32_bf16 v[80:83], v[166:169], v[192:195], v[80:83]
	v_mfma_f32_16x16x32_bf16 v[76:79], v[144:147], v[200:203], v[76:79]
	v_mfma_f32_16x16x32_bf16 v[72:75], v[166:169], v[200:203], v[72:75]
	v_mfma_f32_16x16x32_bf16 v[68:71], v[144:147], v[208:211], v[68:71]
	v_mfma_f32_16x16x32_bf16 v[64:67], v[166:169], v[208:211], v[64:67]
	v_mfma_f32_16x16x32_bf16 v[92:95], v[148:151], v[188:191], v[92:95]
	v_mfma_f32_16x16x32_bf16 v[88:91], v[170:173], v[188:191], v[88:91]
	v_mfma_f32_16x16x32_bf16 v[84:87], v[148:151], v[196:199], v[84:87]
	v_mfma_f32_16x16x32_bf16 v[80:83], v[170:173], v[196:199], v[80:83]
	v_mfma_f32_16x16x32_bf16 v[76:79], v[148:151], v[204:207], v[76:79]
	v_mfma_f32_16x16x32_bf16 v[72:75], v[170:173], v[204:207], v[72:75]
	v_mfma_f32_16x16x32_bf16 v[68:71], v[148:151], v[212:215], v[68:71]
	v_mfma_f32_16x16x32_bf16 v[64:67], v[170:173], v[212:215], v[64:67]
	s_barrier
	s_add_i32 s4, s62, s28
	v_lshl_add_u64 v[174:175], v[174:175], 0, s[8:9]
	s_mov_b32 m0, s4
	ds_read_b128 v[184:187], v183 offset:49152
	ds_read_b128 v[188:191], v183 offset:50176
	ds_read_b128 v[192:195], v183 offset:51200
	ds_read_b128 v[196:199], v183 offset:52224
	ds_read_b128 v[200:203], v183 offset:53248
	ds_read_b128 v[204:207], v183 offset:54272
	ds_read_b128 v[208:211], v183 offset:55296
	ds_read_b128 v[212:215], v183 offset:56320
	global_load_lds_dwordx4 v[174:175], off
	s_add_i32 m0, s4, 0x2000
	s_add_u32 s4, s22, 0x40080
	v_lshl_add_u64 v[174:175], v[216:217], 0, s[8:9]
	s_addc_u32 s5, s23, 0
	s_add_i32 s22, s63, s28
	global_load_lds_dwordx4 v[174:175], off
	s_mov_b32 m0, s22
	s_nop 0
	global_load_lds_dwordx4 v156, s[4:5]
	s_add_i32 m0, s22, 0x2000
	s_nop 0
	global_load_lds_dwordx4 v160, s[4:5]
	v_lshl_add_u64 v[174:175], v[218:219], 0, s[8:9]
	s_mov_b32 m0, s42
	s_nop 0
	global_load_lds_dwordx4 v[174:175], off
	v_lshl_add_u64 v[174:175], v[220:221], 0, s[8:9]
	s_mov_b32 m0, s43
	s_nop 0
	global_load_lds_dwordx4 v[174:175], off
	s_waitcnt vmcnt(8) lgkmcnt(0)
	s_barrier
	v_mfma_f32_16x16x32_bf16 v[60:63], v[128:131], v[184:187], v[60:63]
	v_mfma_f32_16x16x32_bf16 v[56:59], v[136:139], v[184:187], v[56:59]
	v_mfma_f32_16x16x32_bf16 v[52:55], v[128:131], v[192:195], v[52:55]
	v_mfma_f32_16x16x32_bf16 v[48:51], v[136:139], v[192:195], v[48:51]
	v_mfma_f32_16x16x32_bf16 v[44:47], v[128:131], v[200:203], v[44:47]
	v_mfma_f32_16x16x32_bf16 v[40:43], v[136:139], v[200:203], v[40:43]
	v_mfma_f32_16x16x32_bf16 v[36:39], v[128:131], v[208:211], v[36:39]
	v_mfma_f32_16x16x32_bf16 v[32:35], v[136:139], v[208:211], v[32:35]
	v_mfma_f32_16x16x32_bf16 v[60:63], v[132:135], v[188:191], v[60:63]
	v_mfma_f32_16x16x32_bf16 v[56:59], v[140:143], v[188:191], v[56:59]
	v_mfma_f32_16x16x32_bf16 v[52:55], v[132:135], v[196:199], v[52:55]
	v_mfma_f32_16x16x32_bf16 v[48:51], v[140:143], v[196:199], v[48:51]
	v_mfma_f32_16x16x32_bf16 v[44:47], v[132:135], v[204:207], v[44:47]
	v_mfma_f32_16x16x32_bf16 v[40:43], v[140:143], v[204:207], v[40:43]
	v_mfma_f32_16x16x32_bf16 v[36:39], v[132:135], v[212:215], v[36:39]
	v_mfma_f32_16x16x32_bf16 v[32:35], v[140:143], v[212:215], v[32:35]
	v_mfma_f32_16x16x32_bf16 v[28:31], v[144:147], v[184:187], v[28:31]
	v_mfma_f32_16x16x32_bf16 v[24:27], v[166:169], v[184:187], v[24:27]
	v_mfma_f32_16x16x32_bf16 v[20:23], v[144:147], v[192:195], v[20:23]
	v_mfma_f32_16x16x32_bf16 v[16:19], v[166:169], v[192:195], v[16:19]
	v_mfma_f32_16x16x32_bf16 v[12:15], v[144:147], v[200:203], v[12:15]
	v_mfma_f32_16x16x32_bf16 v[8:11], v[166:169], v[200:203], v[8:11]
	v_mfma_f32_16x16x32_bf16 v[4:7], v[144:147], v[208:211], v[4:7]
	v_mfma_f32_16x16x32_bf16 v[0:3], v[166:169], v[208:211], v[0:3]
	v_mfma_f32_16x16x32_bf16 v[28:31], v[148:151], v[188:191], v[28:31]
	v_mfma_f32_16x16x32_bf16 v[24:27], v[170:173], v[188:191], v[24:27]
	v_mfma_f32_16x16x32_bf16 v[20:23], v[148:151], v[196:199], v[20:23]
	v_mfma_f32_16x16x32_bf16 v[16:19], v[170:173], v[196:199], v[16:19]
	v_mfma_f32_16x16x32_bf16 v[12:15], v[148:151], v[204:207], v[12:15]
	v_mfma_f32_16x16x32_bf16 v[8:11], v[170:173], v[204:207], v[8:11]
	v_mfma_f32_16x16x32_bf16 v[4:7], v[148:151], v[212:215], v[4:7]
	v_mfma_f32_16x16x32_bf16 v[0:3], v[170:173], v[212:215], v[0:3]
	s_barrier
	s_add_i32 s61, s61, 2
	s_add_u32 s53, s53, 0x100
	s_addc_u32 s60, s60, 0
	s_cmp_gt_u32 s61, 13
	s_mov_b64 s[4:5], s[20:21]
	s_cbranch_scc0 .LBB0_821
	s_and_b64 vcc, exec, s[10:11]
	s_cbranch_vccz .LBB0_824
	s_barrier

; template <class Sched, class Epi, bool ALIGN_EPI, bool SP2>
; __device__ __forceinline__ void gemm_phase(LAS unsigned char* lds, const int K, const int lda, const int ldb, const Sched& S, const Epi& E) {
;     ...
;         if (!has_next) break;
;         bool keep = false;
;         if constexpr (Epi::CAN_KEEP) keep = (cur.kind < 2);
;         if (!keep) {
; #pragma unroll
;         for (int a = 0; a < 2; ++a)
; #pragma unroll
;             for (int b = 0; b < 2; ++b)
; #pragma unroll
;                 for (int m = 0; m < 4; ++m)
; #pragma unroll
;                     for (int n = 0; n < 2; ++n) acc[a][b][m][n] = (f32x4){0.f, 0.f, 0.f, 0.f};
;         }
.LBB0_856:
	s_setprio 0
	s_andn2_b64 vcc, exec, s[18:19]
	s_mov_b64 s[4:5], -1
	s_cbranch_vccnz .LBB0_813
	s_cmp_lt_i32 s51, 2
	s_cbranch_scc1 .LBB0_859
	v_mov_b32_e32 v0, 0
	v_mov_b32_e32 v1, v0
	v_mov_b32_e32 v2, v0
	v_mov_b32_e32 v3, v0
	v_mov_b32_e32 v4, v0
	v_mov_b32_e32 v5, v0
	v_mov_b32_e32 v6, v0
	v_mov_b32_e32 v7, v0
	v_mov_b32_e32 v8, v0
	v_mov_b32_e32 v9, v0
	v_mov_b32_e32 v10, v0
	v_mov_b32_e32 v11, v0
	v_mov_b32_e32 v12, v0
	v_mov_b32_e32 v13, v0
	v_mov_b32_e32 v14, v0
	v_mov_b32_e32 v15, v0
	v_mov_b32_e32 v16, v0
	v_mov_b32_e32 v17, v0
	v_mov_b32_e32 v18, v0
	v_mov_b32_e32 v19, v0
	v_mov_b32_e32 v20, v0
	v_mov_b32_e32 v21, v0
	v_mov_b32_e32 v22, v0
	v_mov_b32_e32 v23, v0
	v_mov_b32_e32 v24, v0
	v_mov_b32_e32 v25, v0
	v_mov_b32_e32 v26, v0
	v_mov_b32_e32 v27, v0
	v_mov_b32_e32 v28, v0
	v_mov_b32_e32 v29, v0
	v_mov_b32_e32 v30, v0
	v_mov_b32_e32 v31, v0
	v_mov_b32_e32 v32, v0
	v_mov_b32_e32 v33, v0
	v_mov_b32_e32 v34, v0
	v_mov_b32_e32 v35, v0
	v_mov_b32_e32 v36, v0
	v_mov_b32_e32 v37, v0
	v_mov_b32_e32 v38, v0
	v_mov_b32_e32 v39, v0
	v_mov_b32_e32 v40, v0
	v_mov_b32_e32 v41, v0
	v_mov_b32_e32 v42, v0
	v_mov_b32_e32 v43, v0
	v_mov_b32_e32 v44, v0
	v_mov_b32_e32 v45, v0
	v_mov_b32_e32 v46, v0
	v_mov_b32_e32 v47, v0
	v_mov_b32_e32 v48, v0
	v_mov_b32_e32 v49, v0
	v_mov_b32_e32 v50, v0
	v_mov_b32_e32 v51, v0
	v_mov_b32_e32 v52, v0
	v_mov_b32_e32 v53, v0
	v_mov_b32_e32 v54, v0
	v_mov_b32_e32 v55, v0
	v_mov_b32_e32 v56, v0
	v_mov_b32_e32 v57, v0
	v_mov_b32_e32 v58, v0
	v_mov_b32_e32 v59, v0
	v_mov_b32_e32 v60, v0
	v_mov_b32_e32 v61, v0
	v_mov_b32_e32 v62, v0
	v_mov_b32_e32 v63, v0
	v_mov_b32_e32 v64, v0
	v_mov_b32_e32 v65, v0
	v_mov_b32_e32 v66, v0
	v_mov_b32_e32 v67, v0
	v_mov_b32_e32 v68, v0
	v_mov_b32_e32 v69, v0
	v_mov_b32_e32 v70, v0
	v_mov_b32_e32 v71, v0
	v_mov_b32_e32 v72, v0
	v_mov_b32_e32 v73, v0
	v_mov_b32_e32 v74, v0
	v_mov_b32_e32 v75, v0
	v_mov_b32_e32 v76, v0
	v_mov_b32_e32 v77, v0
	v_mov_b32_e32 v78, v0
	v_mov_b32_e32 v79, v0
	v_mov_b32_e32 v80, v0
	v_mov_b32_e32 v81, v0
	v_mov_b32_e32 v82, v0
	v_mov_b32_e32 v83, v0
	v_mov_b32_e32 v84, v0
	v_mov_b32_e32 v85, v0
	v_mov_b32_e32 v86, v0
	v_mov_b32_e32 v87, v0
	v_mov_b32_e32 v88, v0
	v_mov_b32_e32 v89, v0
	v_mov_b32_e32 v90, v0
	v_mov_b32_e32 v91, v0
	v_mov_b32_e32 v92, v0
	v_mov_b32_e32 v93, v0
	v_mov_b32_e32 v94, v0
	v_mov_b32_e32 v95, v0
	v_mov_b32_e32 v96, v0
	v_mov_b32_e32 v97, v0
	v_mov_b32_e32 v98, v0
	v_mov_b32_e32 v99, v0
	v_mov_b32_e32 v100, v0
	v_mov_b32_e32 v101, v0
	v_mov_b32_e32 v102, v0
	v_mov_b32_e32 v103, v0
	v_mov_b32_e32 v104, v0
	v_mov_b32_e32 v105, v0
	v_mov_b32_e32 v106, v0
	v_mov_b32_e32 v107, v0
	v_mov_b32_e32 v108, v0
	v_mov_b32_e32 v109, v0
	v_mov_b32_e32 v110, v0
	v_mov_b32_e32 v111, v0
	v_mov_b32_e32 v112, v0
	v_mov_b32_e32 v113, v0
	v_mov_b32_e32 v114, v0
	v_mov_b32_e32 v115, v0
	v_mov_b32_e32 v116, v0
	v_mov_b32_e32 v117, v0
	v_mov_b32_e32 v118, v0
	v_mov_b32_e32 v119, v0
	v_mov_b32_e32 v120, v0
	v_mov_b32_e32 v121, v0
	v_mov_b32_e32 v122, v0
	v_mov_b32_e32 v123, v0
	v_mov_b32_e32 v124, v0
	v_mov_b32_e32 v125, v0
	v_mov_b32_e32 v126, v0
	v_mov_b32_e32 v127, v0
